# peel first K-iteration of P1 and P5 GEMM loops with C=0 MFMAs, drop 128 accumulator zeroing movs per unit
# speedup vs baseline: 1.0059x; 1.0059x over previous
.LBB0_383:
	s_ashr_i32 s67, s66, 31
	s_lshl_b64 s[26:27], s[66:67], 19
	s_add_u32 s26, s40, s26
	s_addc_u32 s27, s41, s27
	s_and_b64 s[34:35], s[8:9], exec
	s_cselect_b32 s34, s27, s5
	s_cselect_b32 s35, s26, s4
	s_ashr_i32 s29, s28, 31
	s_lshl_b64 s[38:39], s[28:29], 19
	s_add_u32 s62, s10, s38
	s_addc_u32 s63, s11, s39
	s_and_b64 s[38:39], s[8:9], exec
	s_cselect_b32 s29, s63, s83
	s_cselect_b32 s38, s62, s82
	s_add_u32 s39, s82, 0x100
	s_addc_u32 s67, s83, 0
	s_mov_b32 s94, -2
	s_mov_b64 vcc, 0
	s_waitcnt vmcnt(0)
	v_lshl_add_u64 v[132:133], s[4:5], 0, v[168:169]
	ds_read_b128 v[134:137], v199
	ds_read_b128 v[138:141], v200
	ds_read_b128 v[142:145], v201
	ds_read_b128 v[146:149], v202
	ds_read_b128 v[150:153], v203
	ds_read_b128 v[174:177], v204
	ds_read_b128 v[178:181], v205
	ds_read_b128 v[182:185], v206
	s_add_u32 s24, s4, vcc_lo
	s_addc_u32 s25, s5, vcc_hi
	s_add_u32 s24, s24, 0x100
	s_addc_u32 s25, s25, 0
	s_add_u32 s82, s39, vcc_lo
	s_addc_u32 s83, s67, vcc_hi
	s_cmpk_eq_i32 vcc_lo, 0x700
	s_cselect_b32 s87, s29, s83
	s_cselect_b32 s86, s38, s82
	s_cselect_b32 s83, s34, s25
	s_cselect_b32 s82, s35, s24
	v_lshl_add_u64 v[154:155], v[132:133], 0, vcc
	v_lshl_add_u64 v[250:251], v[154:155], 0, s[48:49]
	s_add_i32 m0, s79, 0x8000
	s_mov_b64 s[24:25], 0x20080
	ds_read_b128 v[218:221], v207
	ds_read_b128 v[222:225], v207 offset:2048
	ds_read_b128 v[226:229], v208
	ds_read_b128 v[230:233], v208 offset:2048
	ds_read_b128 v[234:237], v207 offset:4096
	ds_read_b128 v[238:241], v207 offset:6144
	ds_read_b128 v[242:245], v208 offset:4096
	ds_read_b128 v[246:249], v208 offset:6144
	global_load_lds_dwordx4 v[250:251], off
	v_lshl_add_u64 v[250:251], v[154:155], 0, s[24:25]
	s_add_i32 m0, s79, 0xa000
	s_mov_b64 s[24:25], 0x60080
	global_load_lds_dwordx4 v[250:251], off
	v_lshl_add_u64 v[250:251], v[154:155], 0, s[50:51]
	s_add_i32 m0, s79, 0xc000
	v_lshl_add_u64 v[154:155], v[154:155], 0, s[24:25]
	global_load_lds_dwordx4 v[250:251], off
	s_add_i32 m0, s79, 0xe000
	s_nop 0
	global_load_lds_dwordx4 v[154:155], off
	s_waitcnt vmcnt(8)
	s_waitcnt lgkmcnt(0)
	s_barrier
	v_mfma_f32_16x16x32_bf16 v[128:131], v[134:137], v[218:221], 0
	v_mfma_f32_16x16x32_bf16 v[124:127], v[142:145], v[218:221], 0
	v_mfma_f32_16x16x32_bf16 v[112:115], v[134:137], v[222:225], 0
	v_mfma_f32_16x16x32_bf16 v[108:111], v[142:145], v[222:225], 0
	v_mfma_f32_16x16x32_bf16 v[96:99], v[134:137], v[234:237], 0
	v_mfma_f32_16x16x32_bf16 v[92:95], v[142:145], v[234:237], 0
	v_mfma_f32_16x16x32_bf16 v[80:83], v[134:137], v[238:241], 0
	v_mfma_f32_16x16x32_bf16 v[76:79], v[142:145], v[238:241], 0
	v_mfma_f32_16x16x32_bf16 v[128:131], v[138:141], v[226:229], v[128:131]
	v_mfma_f32_16x16x32_bf16 v[124:127], v[146:149], v[226:229], v[124:127]
	v_mfma_f32_16x16x32_bf16 v[112:115], v[138:141], v[230:233], v[112:115]
	v_mfma_f32_16x16x32_bf16 v[108:111], v[146:149], v[230:233], v[108:111]
	v_mfma_f32_16x16x32_bf16 v[96:99], v[138:141], v[242:245], v[96:99]
	v_mfma_f32_16x16x32_bf16 v[92:95], v[146:149], v[242:245], v[92:95]
	v_mfma_f32_16x16x32_bf16 v[80:83], v[138:141], v[246:249], v[80:83]
	v_mfma_f32_16x16x32_bf16 v[76:79], v[146:149], v[246:249], v[76:79]
	v_mfma_f32_16x16x32_bf16 v[120:123], v[150:153], v[218:221], 0
	v_mfma_f32_16x16x32_bf16 v[116:119], v[178:181], v[218:221], 0
	v_mfma_f32_16x16x32_bf16 v[104:107], v[150:153], v[222:225], 0
	v_mfma_f32_16x16x32_bf16 v[100:103], v[178:181], v[222:225], 0
	v_mfma_f32_16x16x32_bf16 v[88:91], v[150:153], v[234:237], 0
	v_mfma_f32_16x16x32_bf16 v[84:87], v[178:181], v[234:237], 0
	v_mfma_f32_16x16x32_bf16 v[72:75], v[150:153], v[238:241], 0
	v_mfma_f32_16x16x32_bf16 v[68:71], v[178:181], v[238:241], 0
	v_mfma_f32_16x16x32_bf16 v[120:123], v[174:177], v[226:229], v[120:123]
	v_mfma_f32_16x16x32_bf16 v[116:119], v[182:185], v[226:229], v[116:119]
	v_mfma_f32_16x16x32_bf16 v[104:107], v[174:177], v[230:233], v[104:107]
	v_mfma_f32_16x16x32_bf16 v[100:103], v[182:185], v[230:233], v[100:103]
	v_mfma_f32_16x16x32_bf16 v[88:91], v[174:177], v[242:245], v[88:91]
	v_mfma_f32_16x16x32_bf16 v[84:87], v[182:185], v[242:245], v[84:87]
	v_mfma_f32_16x16x32_bf16 v[72:75], v[174:177], v[246:249], v[72:75]
	v_mfma_f32_16x16x32_bf16 v[68:71], v[182:185], v[246:249], v[68:71]
	s_barrier
	s_add_i32 s24, s1, s77
	v_lshl_add_u64 v[154:155], s[86:87], 0, v[158:159]
	s_mov_b32 m0, s24
	ds_read_b128 v[218:221], v207 offset:16384
	ds_read_b128 v[222:225], v207 offset:18432
	ds_read_b128 v[226:229], v208 offset:16384
	ds_read_b128 v[230:233], v208 offset:18432
	ds_read_b128 v[234:237], v207 offset:20480
	ds_read_b128 v[238:241], v207 offset:22528
	ds_read_b128 v[242:245], v208 offset:20480
	ds_read_b128 v[246:249], v208 offset:22528
	global_load_lds_dwordx4 v[154:155], off
	v_lshl_add_u64 v[250:251], v[154:155], 0, s[14:15]
	s_add_i32 m0, s24, 0x2000
	s_add_i32 s24, s12, s77
	global_load_lds_dwordx4 v[250:251], off
	v_lshl_add_u64 v[250:251], v[154:155], 0, s[16:17]
	s_mov_b32 m0, s24
	s_nop 0
	global_load_lds_dwordx4 v[250:251], off
	v_lshl_add_u64 v[250:251], v[154:155], 0, s[18:19]
	s_add_i32 m0, s24, 0x2000
	s_nop 0
	global_load_lds_dwordx4 v[250:251], off
	s_waitcnt vmcnt(4)
	s_waitcnt lgkmcnt(0)
	s_barrier
	v_mfma_f32_16x16x32_bf16 v[64:67], v[134:137], v[218:221], 0
	v_mfma_f32_16x16x32_bf16 v[60:63], v[142:145], v[218:221], 0
	v_mfma_f32_16x16x32_bf16 v[48:51], v[134:137], v[222:225], 0
	v_mfma_f32_16x16x32_bf16 v[44:47], v[142:145], v[222:225], 0
	v_mfma_f32_16x16x32_bf16 v[32:35], v[134:137], v[234:237], 0
	v_mfma_f32_16x16x32_bf16 v[28:31], v[142:145], v[234:237], 0
	v_mfma_f32_16x16x32_bf16 v[16:19], v[134:137], v[238:241], 0
	v_mfma_f32_16x16x32_bf16 v[12:15], v[142:145], v[238:241], 0
	v_mfma_f32_16x16x32_bf16 v[64:67], v[138:141], v[226:229], v[64:67]
	v_mfma_f32_16x16x32_bf16 v[60:63], v[146:149], v[226:229], v[60:63]
	v_mfma_f32_16x16x32_bf16 v[48:51], v[138:141], v[230:233], v[48:51]
	v_mfma_f32_16x16x32_bf16 v[44:47], v[146:149], v[230:233], v[44:47]
	v_mfma_f32_16x16x32_bf16 v[32:35], v[138:141], v[242:245], v[32:35]
	v_mfma_f32_16x16x32_bf16 v[28:31], v[146:149], v[242:245], v[28:31]
	v_mfma_f32_16x16x32_bf16 v[16:19], v[138:141], v[246:249], v[16:19]
	v_mfma_f32_16x16x32_bf16 v[12:15], v[146:149], v[246:249], v[12:15]
	v_mfma_f32_16x16x32_bf16 v[56:59], v[150:153], v[218:221], 0
	v_mfma_f32_16x16x32_bf16 v[52:55], v[178:181], v[218:221], 0
	v_mfma_f32_16x16x32_bf16 v[40:43], v[150:153], v[222:225], 0
	v_mfma_f32_16x16x32_bf16 v[36:39], v[178:181], v[222:225], 0
	v_mfma_f32_16x16x32_bf16 v[24:27], v[150:153], v[234:237], 0
	v_mfma_f32_16x16x32_bf16 v[20:23], v[178:181], v[234:237], 0
	v_mfma_f32_16x16x32_bf16 v[8:11], v[150:153], v[238:241], 0
	v_mfma_f32_16x16x32_bf16 v[4:7], v[178:181], v[238:241], 0
	v_mfma_f32_16x16x32_bf16 v[56:59], v[174:177], v[226:229], v[56:59]
	v_mfma_f32_16x16x32_bf16 v[52:55], v[182:185], v[226:229], v[52:55]
	v_mfma_f32_16x16x32_bf16 v[40:43], v[174:177], v[230:233], v[40:43]
	v_mfma_f32_16x16x32_bf16 v[36:39], v[182:185], v[230:233], v[36:39]
	v_mfma_f32_16x16x32_bf16 v[24:27], v[174:177], v[242:245], v[24:27]
	v_mfma_f32_16x16x32_bf16 v[20:23], v[182:185], v[242:245], v[20:23]
	v_mfma_f32_16x16x32_bf16 v[8:11], v[174:177], v[246:249], v[8:11]
	v_mfma_f32_16x16x32_bf16 v[4:7], v[182:185], v[246:249], v[4:7]
	s_barrier
	ds_read_b128 v[134:137], v213
	ds_read_b128 v[138:141], v214
	ds_read_b128 v[142:145], v209
	ds_read_b128 v[146:149], v210
	ds_read_b128 v[150:153], v215
	ds_read_b128 v[174:177], v216
	ds_read_b128 v[178:181], v211
	ds_read_b128 v[182:185], v212
	s_mov_b32 m0, s79
	v_lshl_add_u64 v[250:251], s[82:83], 0, v[0:1]
	ds_read_b128 v[218:221], v207 offset:32768
	ds_read_b128 v[222:225], v207 offset:34816
	ds_read_b128 v[226:229], v208 offset:32768
	ds_read_b128 v[230:233], v208 offset:34816
	ds_read_b128 v[234:237], v207 offset:36864
	ds_read_b128 v[238:241], v207 offset:38912
	ds_read_b128 v[242:245], v208 offset:36864
	ds_read_b128 v[246:249], v208 offset:38912
	global_load_lds_dwordx4 v[250:251], off
	v_lshl_add_u64 v[252:253], v[250:251], 0, s[20:21]
	s_mov_b32 m0, s81
	s_nop 0
	global_load_lds_dwordx4 v[252:253], off
	v_lshl_add_u64 v[252:253], v[250:251], 0, s[14:15]
	s_mov_b32 m0, s97
	v_lshl_add_u64 v[250:251], v[250:251], 0, s[22:23]
	global_load_lds_dwordx4 v[252:253], off
	s_mov_b32 m0, s64
	s_nop 0
	global_load_lds_dwordx4 v[250:251], off
	s_waitcnt vmcnt(8)
	s_waitcnt lgkmcnt(0)
	s_barrier
	v_mfma_f32_16x16x32_bf16 v[128:131], v[134:137], v[218:221], v[128:131]
	v_mfma_f32_16x16x32_bf16 v[124:127], v[142:145], v[218:221], v[124:127]
	v_mfma_f32_16x16x32_bf16 v[112:115], v[134:137], v[222:225], v[112:115]
	v_mfma_f32_16x16x32_bf16 v[108:111], v[142:145], v[222:225], v[108:111]
	v_mfma_f32_16x16x32_bf16 v[96:99], v[134:137], v[234:237], v[96:99]
	v_mfma_f32_16x16x32_bf16 v[92:95], v[142:145], v[234:237], v[92:95]
	v_mfma_f32_16x16x32_bf16 v[80:83], v[134:137], v[238:241], v[80:83]
	v_mfma_f32_16x16x32_bf16 v[76:79], v[142:145], v[238:241], v[76:79]
	v_mfma_f32_16x16x32_bf16 v[128:131], v[138:141], v[226:229], v[128:131]
	v_mfma_f32_16x16x32_bf16 v[124:127], v[146:149], v[226:229], v[124:127]
	v_mfma_f32_16x16x32_bf16 v[112:115], v[138:141], v[230:233], v[112:115]
	v_mfma_f32_16x16x32_bf16 v[108:111], v[146:149], v[230:233], v[108:111]
	v_mfma_f32_16x16x32_bf16 v[96:99], v[138:141], v[242:245], v[96:99]
	v_mfma_f32_16x16x32_bf16 v[92:95], v[146:149], v[242:245], v[92:95]
	v_mfma_f32_16x16x32_bf16 v[80:83], v[138:141], v[246:249], v[80:83]
	v_mfma_f32_16x16x32_bf16 v[76:79], v[146:149], v[246:249], v[76:79]
	v_mfma_f32_16x16x32_bf16 v[120:123], v[150:153], v[218:221], v[120:123]
	v_mfma_f32_16x16x32_bf16 v[116:119], v[178:181], v[218:221], v[116:119]
	v_mfma_f32_16x16x32_bf16 v[104:107], v[150:153], v[222:225], v[104:107]
	v_mfma_f32_16x16x32_bf16 v[100:103], v[178:181], v[222:225], v[100:103]
	v_mfma_f32_16x16x32_bf16 v[88:91], v[150:153], v[234:237], v[88:91]
	v_mfma_f32_16x16x32_bf16 v[84:87], v[178:181], v[234:237], v[84:87]
	v_mfma_f32_16x16x32_bf16 v[72:75], v[150:153], v[238:241], v[72:75]
	v_mfma_f32_16x16x32_bf16 v[68:71], v[178:181], v[238:241], v[68:71]
	v_mfma_f32_16x16x32_bf16 v[120:123], v[174:177], v[226:229], v[120:123]
	v_mfma_f32_16x16x32_bf16 v[116:119], v[182:185], v[226:229], v[116:119]
	v_mfma_f32_16x16x32_bf16 v[104:107], v[174:177], v[230:233], v[104:107]
	v_mfma_f32_16x16x32_bf16 v[100:103], v[182:185], v[230:233], v[100:103]
	v_mfma_f32_16x16x32_bf16 v[88:91], v[174:177], v[242:245], v[88:91]
	v_mfma_f32_16x16x32_bf16 v[84:87], v[182:185], v[242:245], v[84:87]
	v_mfma_f32_16x16x32_bf16 v[72:75], v[174:177], v[246:249], v[72:75]
	v_mfma_f32_16x16x32_bf16 v[68:71], v[182:185], v[246:249], v[68:71]
	s_barrier
	s_add_i32 s24, s70, s77
	v_lshl_add_u64 v[250:251], v[154:155], 0, s[48:49]
	s_mov_b32 m0, s24
	ds_read_b128 v[218:221], v207 offset:49152
	ds_read_b128 v[222:225], v207 offset:51200
	ds_read_b128 v[226:229], v208 offset:49152
	ds_read_b128 v[230:233], v208 offset:51200
	ds_read_b128 v[234:237], v207 offset:53248
	ds_read_b128 v[238:241], v207 offset:55296
	ds_read_b128 v[242:245], v208 offset:53248
	ds_read_b128 v[246:249], v208 offset:55296
	global_load_lds_dwordx4 v[250:251], off
	v_lshl_add_u64 v[250:251], v[154:155], 0, s[50:51]
	s_add_i32 m0, s24, 0x2000
	s_add_i32 s24, s71, s77
	global_load_lds_dwordx4 v[250:251], off
	v_lshl_add_u64 v[250:251], v[154:155], 0, s[52:53]
	s_mov_b32 m0, s24
	v_lshl_add_u64 v[154:155], v[154:155], 0, s[54:55]
	global_load_lds_dwordx4 v[250:251], off
	s_add_i32 m0, s24, 0x2000
	s_nop 0
	global_load_lds_dwordx4 v[154:155], off
	s_waitcnt vmcnt(4)
	s_waitcnt lgkmcnt(0)
	s_barrier
	v_mfma_f32_16x16x32_bf16 v[64:67], v[134:137], v[218:221], v[64:67]
	v_mfma_f32_16x16x32_bf16 v[60:63], v[142:145], v[218:221], v[60:63]
	v_mfma_f32_16x16x32_bf16 v[48:51], v[134:137], v[222:225], v[48:51]
	v_mfma_f32_16x16x32_bf16 v[44:47], v[142:145], v[222:225], v[44:47]
	v_mfma_f32_16x16x32_bf16 v[32:35], v[134:137], v[234:237], v[32:35]
	v_mfma_f32_16x16x32_bf16 v[28:31], v[142:145], v[234:237], v[28:31]
	v_mfma_f32_16x16x32_bf16 v[16:19], v[134:137], v[238:241], v[16:19]
	v_mfma_f32_16x16x32_bf16 v[12:15], v[142:145], v[238:241], v[12:15]
	v_mfma_f32_16x16x32_bf16 v[64:67], v[138:141], v[226:229], v[64:67]
	v_mfma_f32_16x16x32_bf16 v[60:63], v[146:149], v[226:229], v[60:63]
	v_mfma_f32_16x16x32_bf16 v[48:51], v[138:141], v[230:233], v[48:51]
	v_mfma_f32_16x16x32_bf16 v[44:47], v[146:149], v[230:233], v[44:47]
	v_mfma_f32_16x16x32_bf16 v[32:35], v[138:141], v[242:245], v[32:35]
	v_mfma_f32_16x16x32_bf16 v[28:31], v[146:149], v[242:245], v[28:31]
	v_mfma_f32_16x16x32_bf16 v[16:19], v[138:141], v[246:249], v[16:19]
	v_mfma_f32_16x16x32_bf16 v[12:15], v[146:149], v[246:249], v[12:15]
	v_mfma_f32_16x16x32_bf16 v[56:59], v[150:153], v[218:221], v[56:59]
	v_mfma_f32_16x16x32_bf16 v[52:55], v[178:181], v[218:221], v[52:55]
	v_mfma_f32_16x16x32_bf16 v[40:43], v[150:153], v[222:225], v[40:43]
	v_mfma_f32_16x16x32_bf16 v[36:39], v[178:181], v[222:225], v[36:39]
	v_mfma_f32_16x16x32_bf16 v[24:27], v[150:153], v[234:237], v[24:27]
	v_mfma_f32_16x16x32_bf16 v[20:23], v[178:181], v[234:237], v[20:23]
	v_mfma_f32_16x16x32_bf16 v[8:11], v[150:153], v[238:241], v[8:11]
	v_mfma_f32_16x16x32_bf16 v[4:7], v[178:181], v[238:241], v[4:7]
	v_mfma_f32_16x16x32_bf16 v[56:59], v[174:177], v[226:229], v[56:59]
	v_mfma_f32_16x16x32_bf16 v[52:55], v[182:185], v[226:229], v[52:55]
	v_mfma_f32_16x16x32_bf16 v[40:43], v[174:177], v[230:233], v[40:43]
	v_mfma_f32_16x16x32_bf16 v[36:39], v[182:185], v[230:233], v[36:39]
	v_mfma_f32_16x16x32_bf16 v[24:27], v[174:177], v[242:245], v[24:27]
	v_mfma_f32_16x16x32_bf16 v[20:23], v[182:185], v[242:245], v[20:23]
	v_mfma_f32_16x16x32_bf16 v[8:11], v[174:177], v[246:249], v[8:11]
	v_mfma_f32_16x16x32_bf16 v[4:7], v[182:185], v[246:249], v[4:7]
	s_barrier
	s_add_i32 s94, s94, 2
	s_add_u32 vcc_lo, vcc_lo, 0x100
	s_addc_u32 vcc_hi, vcc_hi, 0
	s_cmp_gt_u32 s94, 13

.LBB0_1134:
	s_ashr_i32 s57, s56, 31
	s_lshl_b64 s[60:61], s[56:57], 19
	s_add_u32 s60, s42, s60
	s_addc_u32 s61, s43, s61
	s_and_b64 s[62:63], s[10:11], exec
	s_cselect_b32 s57, s61, s27
	s_cselect_b32 s79, s60, s26
	s_ashr_i32 s59, s58, 31
	s_lshl_b64 s[62:63], s[58:59], 19
	v_readlane_b32 s70, v254, 7
	v_readlane_b32 s71, v254, 8
	s_add_u32 s62, s70, s62
	s_addc_u32 s63, s71, s63
	s_and_b64 s[70:71], s[10:11], exec
	s_cselect_b32 s59, s63, s69
	s_cselect_b32 s80, s62, s68
	s_add_u32 s81, s68, 0x100
	v_lshl_add_u64 v[138:139], s[26:27], 0, v[132:133]
	s_addc_u32 s82, s69, 0
	s_mov_b32 s83, -2
	s_mov_b64 s[68:69], 0
	ds_read_b128 v[168:171], v145
	ds_read_b128 v[174:177], v146
	ds_read_b128 v[178:181], v147
	ds_read_b128 v[182:185], v148
	ds_read_b128 v[194:197], v149
	ds_read_b128 v[198:201], v150
	ds_read_b128 v[202:205], v151
	ds_read_b128 v[206:209], v152
	s_add_u32 s70, s26, s68
	s_addc_u32 s71, s27, s69
	s_add_u32 s70, s70, 0x100
	s_addc_u32 s71, s71, 0
	s_add_u32 s84, s81, s68
	s_addc_u32 s85, s82, s69
	s_cmpk_eq_i32 s68, 0x700
	s_cselect_b32 s85, s59, s85
	s_cselect_b32 s84, s80, s84
	s_cselect_b32 s71, s57, s71
	s_cselect_b32 s70, s79, s70
	v_lshl_add_u64 v[140:141], v[138:139], 0, s[68:69]
	v_lshl_add_u64 v[242:243], v[140:141], 0, s[22:23]
	s_add_i32 m0, s34, 0x8000
	s_mov_b64 s[86:87], 0x20080
	ds_read_b128 v[210:213], v153
	ds_read_b128 v[214:217], v153 offset:2048
	ds_read_b128 v[218:221], v154
	ds_read_b128 v[222:225], v154 offset:2048
	ds_read_b128 v[226:229], v153 offset:4096
	ds_read_b128 v[230:233], v153 offset:6144
	ds_read_b128 v[234:237], v154 offset:4096
	ds_read_b128 v[238:241], v154 offset:6144
	global_load_lds_dwordx4 v[242:243], off
	v_lshl_add_u64 v[242:243], v[140:141], 0, s[86:87]
	s_add_i32 m0, s34, 0xa000
	s_mov_b64 s[86:87], 0x60080
	global_load_lds_dwordx4 v[242:243], off
	v_lshl_add_u64 v[242:243], v[140:141], 0, s[24:25]
	s_add_i32 m0, s34, 0xc000
	v_lshl_add_u64 v[140:141], v[140:141], 0, s[86:87]
	global_load_lds_dwordx4 v[242:243], off
	s_add_i32 m0, s34, 0xe000
	s_nop 0
	global_load_lds_dwordx4 v[140:141], off
	s_waitcnt vmcnt(8)
	s_waitcnt lgkmcnt(0)
	s_barrier
	v_mfma_f32_16x16x32_bf16 v[128:131], v[168:171], v[210:213], 0
	v_mfma_f32_16x16x32_bf16 v[124:127], v[178:181], v[210:213], 0
	v_mfma_f32_16x16x32_bf16 v[112:115], v[168:171], v[214:217], 0
	v_mfma_f32_16x16x32_bf16 v[108:111], v[178:181], v[214:217], 0
	v_mfma_f32_16x16x32_bf16 v[96:99], v[168:171], v[226:229], 0
	v_mfma_f32_16x16x32_bf16 v[92:95], v[178:181], v[226:229], 0
	v_mfma_f32_16x16x32_bf16 v[80:83], v[168:171], v[230:233], 0
	v_mfma_f32_16x16x32_bf16 v[76:79], v[178:181], v[230:233], 0
	v_mfma_f32_16x16x32_bf16 v[128:131], v[174:177], v[218:221], v[128:131]
	v_mfma_f32_16x16x32_bf16 v[124:127], v[182:185], v[218:221], v[124:127]
	v_mfma_f32_16x16x32_bf16 v[112:115], v[174:177], v[222:225], v[112:115]
	v_mfma_f32_16x16x32_bf16 v[108:111], v[182:185], v[222:225], v[108:111]
	v_mfma_f32_16x16x32_bf16 v[96:99], v[174:177], v[234:237], v[96:99]
	v_mfma_f32_16x16x32_bf16 v[92:95], v[182:185], v[234:237], v[92:95]
	v_mfma_f32_16x16x32_bf16 v[80:83], v[174:177], v[238:241], v[80:83]
	v_mfma_f32_16x16x32_bf16 v[76:79], v[182:185], v[238:241], v[76:79]
	v_mfma_f32_16x16x32_bf16 v[120:123], v[194:197], v[210:213], 0
	v_mfma_f32_16x16x32_bf16 v[116:119], v[202:205], v[210:213], 0
	v_mfma_f32_16x16x32_bf16 v[104:107], v[194:197], v[214:217], 0
	v_mfma_f32_16x16x32_bf16 v[100:103], v[202:205], v[214:217], 0
	v_mfma_f32_16x16x32_bf16 v[88:91], v[194:197], v[226:229], 0
	v_mfma_f32_16x16x32_bf16 v[84:87], v[202:205], v[226:229], 0
	v_mfma_f32_16x16x32_bf16 v[72:75], v[194:197], v[230:233], 0
	v_mfma_f32_16x16x32_bf16 v[68:71], v[202:205], v[230:233], 0
	v_mfma_f32_16x16x32_bf16 v[120:123], v[198:201], v[218:221], v[120:123]
	v_mfma_f32_16x16x32_bf16 v[116:119], v[206:209], v[218:221], v[116:119]
	v_mfma_f32_16x16x32_bf16 v[104:107], v[198:201], v[222:225], v[104:107]
	v_mfma_f32_16x16x32_bf16 v[100:103], v[206:209], v[222:225], v[100:103]
	v_mfma_f32_16x16x32_bf16 v[88:91], v[198:201], v[234:237], v[88:91]
	v_mfma_f32_16x16x32_bf16 v[84:87], v[206:209], v[234:237], v[84:87]
	v_mfma_f32_16x16x32_bf16 v[72:75], v[198:201], v[238:241], v[72:75]
	v_mfma_f32_16x16x32_bf16 v[68:71], v[206:209], v[238:241], v[68:71]
	s_barrier
	v_lshl_add_u64 v[140:141], s[84:85], 0, v[158:159]
	s_add_i32 s84, s67, s3
	s_mov_b32 m0, s84
	ds_read_b128 v[210:213], v153 offset:16384
	ds_read_b128 v[214:217], v153 offset:18432
	ds_read_b128 v[218:221], v154 offset:16384
	ds_read_b128 v[222:225], v154 offset:18432
	ds_read_b128 v[226:229], v153 offset:20480
	ds_read_b128 v[230:233], v153 offset:22528
	ds_read_b128 v[234:237], v154 offset:20480
	ds_read_b128 v[238:241], v154 offset:22528
	global_load_lds_dwordx4 v[140:141], off
	v_lshl_add_u64 v[242:243], v[140:141], 0, s[0:1]
	s_add_i32 m0, s84, 0x2000
	s_add_i32 s84, s72, s3
	global_load_lds_dwordx4 v[242:243], off
	v_lshl_add_u64 v[242:243], v[140:141], 0, s[12:13]
	s_mov_b32 m0, s84
	s_nop 0
	global_load_lds_dwordx4 v[242:243], off
	v_lshl_add_u64 v[242:243], v[140:141], 0, s[14:15]
	s_add_i32 m0, s84, 0x2000
	s_nop 0
	global_load_lds_dwordx4 v[242:243], off
	s_waitcnt vmcnt(4)
	s_waitcnt lgkmcnt(0)
	s_barrier
	v_mfma_f32_16x16x32_bf16 v[64:67], v[168:171], v[210:213], 0
	v_mfma_f32_16x16x32_bf16 v[60:63], v[178:181], v[210:213], 0
	v_mfma_f32_16x16x32_bf16 v[48:51], v[168:171], v[214:217], 0
	v_mfma_f32_16x16x32_bf16 v[44:47], v[178:181], v[214:217], 0
	v_mfma_f32_16x16x32_bf16 v[32:35], v[168:171], v[226:229], 0
	v_mfma_f32_16x16x32_bf16 v[28:31], v[178:181], v[226:229], 0
	v_mfma_f32_16x16x32_bf16 v[16:19], v[168:171], v[230:233], 0
	v_mfma_f32_16x16x32_bf16 v[12:15], v[178:181], v[230:233], 0
	v_mfma_f32_16x16x32_bf16 v[64:67], v[174:177], v[218:221], v[64:67]
	v_mfma_f32_16x16x32_bf16 v[60:63], v[182:185], v[218:221], v[60:63]
	v_mfma_f32_16x16x32_bf16 v[48:51], v[174:177], v[222:225], v[48:51]
	v_mfma_f32_16x16x32_bf16 v[44:47], v[182:185], v[222:225], v[44:47]
	v_mfma_f32_16x16x32_bf16 v[32:35], v[174:177], v[234:237], v[32:35]
	v_mfma_f32_16x16x32_bf16 v[28:31], v[182:185], v[234:237], v[28:31]
	v_mfma_f32_16x16x32_bf16 v[16:19], v[174:177], v[238:241], v[16:19]
	v_mfma_f32_16x16x32_bf16 v[12:15], v[182:185], v[238:241], v[12:15]
	v_mfma_f32_16x16x32_bf16 v[56:59], v[194:197], v[210:213], 0
	v_mfma_f32_16x16x32_bf16 v[52:55], v[202:205], v[210:213], 0
	v_mfma_f32_16x16x32_bf16 v[40:43], v[194:197], v[214:217], 0
	v_mfma_f32_16x16x32_bf16 v[36:39], v[202:205], v[214:217], 0
	v_mfma_f32_16x16x32_bf16 v[24:27], v[194:197], v[226:229], 0
	v_mfma_f32_16x16x32_bf16 v[20:23], v[202:205], v[226:229], 0
	v_mfma_f32_16x16x32_bf16 v[8:11], v[194:197], v[230:233], 0
	v_mfma_f32_16x16x32_bf16 v[4:7], v[202:205], v[230:233], 0
	v_mfma_f32_16x16x32_bf16 v[56:59], v[198:201], v[218:221], v[56:59]
	v_mfma_f32_16x16x32_bf16 v[52:55], v[206:209], v[218:221], v[52:55]
	v_mfma_f32_16x16x32_bf16 v[40:43], v[198:201], v[222:225], v[40:43]
	v_mfma_f32_16x16x32_bf16 v[36:39], v[206:209], v[222:225], v[36:39]
	v_mfma_f32_16x16x32_bf16 v[24:27], v[198:201], v[234:237], v[24:27]
	v_mfma_f32_16x16x32_bf16 v[20:23], v[206:209], v[234:237], v[20:23]
	v_mfma_f32_16x16x32_bf16 v[8:11], v[198:201], v[238:241], v[8:11]
	v_mfma_f32_16x16x32_bf16 v[4:7], v[206:209], v[238:241], v[4:7]
	s_barrier
	ds_read_b128 v[168:171], v163
	ds_read_b128 v[174:177], v164
	ds_read_b128 v[178:181], v155
	ds_read_b128 v[182:185], v160
	ds_read_b128 v[194:197], v165
	ds_read_b128 v[198:201], v166
	ds_read_b128 v[202:205], v161
	ds_read_b128 v[206:209], v162
	s_mov_b32 m0, s34
	v_lshl_add_u64 v[242:243], s[70:71], 0, v[0:1]
	ds_read_b128 v[210:213], v153 offset:32768
	ds_read_b128 v[214:217], v153 offset:34816
	ds_read_b128 v[218:221], v154 offset:32768
	ds_read_b128 v[222:225], v154 offset:34816
	ds_read_b128 v[226:229], v153 offset:36864
	ds_read_b128 v[230:233], v153 offset:38912
	ds_read_b128 v[234:237], v154 offset:36864
	ds_read_b128 v[238:241], v154 offset:38912
	global_load_lds_dwordx4 v[242:243], off
	v_lshl_add_u64 v[244:245], v[242:243], 0, s[16:17]
	s_mov_b32 m0, s35
	s_nop 0
	global_load_lds_dwordx4 v[244:245], off
	v_lshl_add_u64 v[244:245], v[242:243], 0, s[0:1]
	s_mov_b32 m0, s38
	v_lshl_add_u64 v[242:243], v[242:243], 0, s[18:19]
	global_load_lds_dwordx4 v[244:245], off
	s_mov_b32 m0, s39
	s_nop 0
	global_load_lds_dwordx4 v[242:243], off
	s_waitcnt vmcnt(8)
	s_waitcnt lgkmcnt(0)
	s_barrier
	v_mfma_f32_16x16x32_bf16 v[128:131], v[168:171], v[210:213], v[128:131]
	v_mfma_f32_16x16x32_bf16 v[124:127], v[178:181], v[210:213], v[124:127]
	v_mfma_f32_16x16x32_bf16 v[112:115], v[168:171], v[214:217], v[112:115]
	v_mfma_f32_16x16x32_bf16 v[108:111], v[178:181], v[214:217], v[108:111]
	v_mfma_f32_16x16x32_bf16 v[96:99], v[168:171], v[226:229], v[96:99]
	v_mfma_f32_16x16x32_bf16 v[92:95], v[178:181], v[226:229], v[92:95]
	v_mfma_f32_16x16x32_bf16 v[80:83], v[168:171], v[230:233], v[80:83]
	v_mfma_f32_16x16x32_bf16 v[76:79], v[178:181], v[230:233], v[76:79]
	v_mfma_f32_16x16x32_bf16 v[128:131], v[174:177], v[218:221], v[128:131]
	v_mfma_f32_16x16x32_bf16 v[124:127], v[182:185], v[218:221], v[124:127]
	v_mfma_f32_16x16x32_bf16 v[112:115], v[174:177], v[222:225], v[112:115]
	v_mfma_f32_16x16x32_bf16 v[108:111], v[182:185], v[222:225], v[108:111]
	v_mfma_f32_16x16x32_bf16 v[96:99], v[174:177], v[234:237], v[96:99]
	v_mfma_f32_16x16x32_bf16 v[92:95], v[182:185], v[234:237], v[92:95]
	v_mfma_f32_16x16x32_bf16 v[80:83], v[174:177], v[238:241], v[80:83]
	v_mfma_f32_16x16x32_bf16 v[76:79], v[182:185], v[238:241], v[76:79]
	v_mfma_f32_16x16x32_bf16 v[120:123], v[194:197], v[210:213], v[120:123]
	v_mfma_f32_16x16x32_bf16 v[116:119], v[202:205], v[210:213], v[116:119]
	v_mfma_f32_16x16x32_bf16 v[104:107], v[194:197], v[214:217], v[104:107]
	v_mfma_f32_16x16x32_bf16 v[100:103], v[202:205], v[214:217], v[100:103]
	v_mfma_f32_16x16x32_bf16 v[88:91], v[194:197], v[226:229], v[88:91]
	v_mfma_f32_16x16x32_bf16 v[84:87], v[202:205], v[226:229], v[84:87]
	v_mfma_f32_16x16x32_bf16 v[72:75], v[194:197], v[230:233], v[72:75]
	v_mfma_f32_16x16x32_bf16 v[68:71], v[202:205], v[230:233], v[68:71]
	v_mfma_f32_16x16x32_bf16 v[120:123], v[198:201], v[218:221], v[120:123]
	v_mfma_f32_16x16x32_bf16 v[116:119], v[206:209], v[218:221], v[116:119]
	v_mfma_f32_16x16x32_bf16 v[104:107], v[198:201], v[222:225], v[104:107]
	v_mfma_f32_16x16x32_bf16 v[100:103], v[206:209], v[222:225], v[100:103]
	v_mfma_f32_16x16x32_bf16 v[88:91], v[198:201], v[234:237], v[88:91]
	v_mfma_f32_16x16x32_bf16 v[84:87], v[206:209], v[234:237], v[84:87]
	v_mfma_f32_16x16x32_bf16 v[72:75], v[198:201], v[238:241], v[72:75]
	v_mfma_f32_16x16x32_bf16 v[68:71], v[206:209], v[238:241], v[68:71]
	s_barrier
	s_add_i32 s70, s73, s3
	v_lshl_add_u64 v[242:243], v[140:141], 0, s[22:23]
	s_mov_b32 m0, s70
	ds_read_b128 v[210:213], v153 offset:49152
	ds_read_b128 v[214:217], v153 offset:51200
	ds_read_b128 v[218:221], v154 offset:49152
	ds_read_b128 v[222:225], v154 offset:51200
	ds_read_b128 v[226:229], v153 offset:53248
	ds_read_b128 v[230:233], v153 offset:55296
	ds_read_b128 v[234:237], v154 offset:53248
	ds_read_b128 v[238:241], v154 offset:55296
	global_load_lds_dwordx4 v[242:243], off
	v_lshl_add_u64 v[242:243], v[140:141], 0, s[24:25]
	s_add_i32 m0, s70, 0x2000
	s_add_i32 s70, s77, s3
	global_load_lds_dwordx4 v[242:243], off
	v_lshl_add_u64 v[242:243], v[140:141], 0, s[28:29]
	s_mov_b32 m0, s70
	v_lshl_add_u64 v[140:141], v[140:141], 0, s[36:37]
	global_load_lds_dwordx4 v[242:243], off
	s_add_i32 m0, s70, 0x2000
	s_nop 0
	global_load_lds_dwordx4 v[140:141], off
	s_waitcnt vmcnt(4)
	s_waitcnt lgkmcnt(0)
	s_barrier
	v_mfma_f32_16x16x32_bf16 v[64:67], v[168:171], v[210:213], v[64:67]
	v_mfma_f32_16x16x32_bf16 v[60:63], v[178:181], v[210:213], v[60:63]
	v_mfma_f32_16x16x32_bf16 v[48:51], v[168:171], v[214:217], v[48:51]
	v_mfma_f32_16x16x32_bf16 v[44:47], v[178:181], v[214:217], v[44:47]
	v_mfma_f32_16x16x32_bf16 v[32:35], v[168:171], v[226:229], v[32:35]
	v_mfma_f32_16x16x32_bf16 v[28:31], v[178:181], v[226:229], v[28:31]
	v_mfma_f32_16x16x32_bf16 v[16:19], v[168:171], v[230:233], v[16:19]
	v_mfma_f32_16x16x32_bf16 v[12:15], v[178:181], v[230:233], v[12:15]
	v_mfma_f32_16x16x32_bf16 v[64:67], v[174:177], v[218:221], v[64:67]
	v_mfma_f32_16x16x32_bf16 v[60:63], v[182:185], v[218:221], v[60:63]
	v_mfma_f32_16x16x32_bf16 v[48:51], v[174:177], v[222:225], v[48:51]
	v_mfma_f32_16x16x32_bf16 v[44:47], v[182:185], v[222:225], v[44:47]
	v_mfma_f32_16x16x32_bf16 v[32:35], v[174:177], v[234:237], v[32:35]
	v_mfma_f32_16x16x32_bf16 v[28:31], v[182:185], v[234:237], v[28:31]
	v_mfma_f32_16x16x32_bf16 v[16:19], v[174:177], v[238:241], v[16:19]
	v_mfma_f32_16x16x32_bf16 v[12:15], v[182:185], v[238:241], v[12:15]
	v_mfma_f32_16x16x32_bf16 v[56:59], v[194:197], v[210:213], v[56:59]
	v_mfma_f32_16x16x32_bf16 v[52:55], v[202:205], v[210:213], v[52:55]
	v_mfma_f32_16x16x32_bf16 v[40:43], v[194:197], v[214:217], v[40:43]
	v_mfma_f32_16x16x32_bf16 v[36:39], v[202:205], v[214:217], v[36:39]
	v_mfma_f32_16x16x32_bf16 v[24:27], v[194:197], v[226:229], v[24:27]
	v_mfma_f32_16x16x32_bf16 v[20:23], v[202:205], v[226:229], v[20:23]
	v_mfma_f32_16x16x32_bf16 v[8:11], v[194:197], v[230:233], v[8:11]
	v_mfma_f32_16x16x32_bf16 v[4:7], v[202:205], v[230:233], v[4:7]
	v_mfma_f32_16x16x32_bf16 v[56:59], v[198:201], v[218:221], v[56:59]
	v_mfma_f32_16x16x32_bf16 v[52:55], v[206:209], v[218:221], v[52:55]
	v_mfma_f32_16x16x32_bf16 v[40:43], v[198:201], v[222:225], v[40:43]
	v_mfma_f32_16x16x32_bf16 v[36:39], v[206:209], v[222:225], v[36:39]
	v_mfma_f32_16x16x32_bf16 v[24:27], v[198:201], v[234:237], v[24:27]
	v_mfma_f32_16x16x32_bf16 v[20:23], v[206:209], v[234:237], v[20:23]
	v_mfma_f32_16x16x32_bf16 v[8:11], v[198:201], v[238:241], v[8:11]
	v_mfma_f32_16x16x32_bf16 v[4:7], v[206:209], v[238:241], v[4:7]
	s_barrier
	s_add_i32 s83, s83, 2
	s_add_u32 s68, s68, 0x100
	s_addc_u32 s69, s69, 0
	s_cmp_gt_u32 s83, 13
